# P5 tiles visited in reverse round order (L^256) so round 0 reads what P4 wrote last
# speedup vs baseline: 1.0263x; 1.0018x over previous
;     __device__ bool next(int i, Unit& u) const { if (!S.next(i >> 1, u)) return false; u.z = i & 1; return true; }
;     __device__ bool next(int i, Unit& u) const { if (!S.next(i, u)) return false; u.z = z; return true; }
; #define PHASE_BEGIN() P.reload(launder_s(kargs)); const int G = sopq(G0), bx = sopq(bx0); const int lane = opq(lane_id()); const int gw = bx * 8 + wave, NGW = G * 8; (void)gw; (void)NGW; (void)lane
; #define PHASE_BEGIN() P.reload(launder_s(kargs)); const int G = sopq(G0), bx = sopq(bx0); const int lane = opq(lane_id()); const int gw = bx * 8 + wave, NGW = G * 8; (void)gw; (void)NGW; (void)lane
;     __device__ bool next(int i, Unit& u) const {
;         const long L = (long)i * G + c; if (L >= nwg) return false;
;         int wgid = (int)L; { const int q = nwg / NXCD, r = nwg % NXCD, xcd = wgid % NXCD, off = wgid / NXCD; wgid = (xcd < r ? xcd * (q + 1) : r * (q + 1) + (xcd - r) * q) + off; }
;         const int nR = tr ? nN : nM, nS = tr ? nM : nN;
;         const int nig = wgm * nS, gid = wgid / nig, f0 = gid * wgm, gsz = (nR - f0) < wgm ? (nR - f0) : wgm;
;         const int pr = f0 + ((wgid % nig) % gsz), ps = (wgid % nig) / gsz;
;         u.pm = tr ? ps : pr; u.pn = tr ? pr : ps; u.z = 0; return true;
; template <int l> __device__ __forceinline__ void layer_phases(LAS unsigned char* lds, Ptrs& P, const XcdBarrier& xbar, KArgs kargs, const int lo, const int hi, const int lane0, const int wave, const int G0, const int bx0) {
;     ...
;         if (IN(pb + 7)) {
;             PHASE_BEGIN();
;             pg8::Gemm g{P.XB1(), P.WPG() + (size_t)l * DM * DM, DM, DM, DM, 0, 0, P.wave}; pg8::StaticOrder S; S.init(M, DM, G, bx, WGM_BF);
;             pg8::EpiPle E{P.X1(), P.T(), P.SSQ() + (size_t)(1 + 2 * l) * M, P.out, P.XB(), P.XB8(), P.SSQ() + (size_t)(2 + 2 * l) * M, l + 1 < DEPTH};
;     ...
;             pg8::gemm_phase<pg8::EpiPle, pg8::StaticOrder, true>(lds, g, S, E);
.LBB0_1334:
	v_readlane_b32 s0, v254, 0
	v_readlane_b32 s2, v254, 2
	s_cmp_lt_i32 s2, 9
	v_readlane_b32 s1, v254, 1
	s_cselect_b64 s[6:7], -1, 0
	s_and_b64 s[0:1], s[6:7], s[44:45]
	s_andn2_b64 vcc, exec, s[0:1]
	v_readlane_b32 s3, v254, 3
	s_cbranch_vccnz .LBB0_1377
	s_waitcnt vmcnt(0)
	v_mbcnt_lo_u32_b32 v0, -1, 0
	v_readlane_b32 s0, v254, 7
	v_readlane_b32 s2, v254, 4
	v_mbcnt_hi_u32_b32 v162, -1, v0
	v_readlane_b32 s1, v254, 8
	s_mov_b32 s18, s2
	s_mov_b32 s19, s79
	s_cmp_eq_u32 s18, 0x100
	s_cselect_b32 s97, 0x100, 0
	s_xor_b32 s19, s19, s97
	v_mov_b32_e32 v0, v162
	v_readlane_b32 s3, v254, 5
	v_readlane_b32 s2, v254, 15
	s_cmpk_lt_i32 s19, 0x200
	s_nop 0
	v_lshl_or_b32 v0, s2, 6, v162
	s_cselect_b64 s[2:3], -1, 0
	s_cmpk_gt_i32 s19, 0x1ff
	s_cbranch_scc1 .LBB0_1341
	s_ashr_i32 s4, s19, 31
	s_lshr_b32 s4, s4, 29
	s_waitcnt lgkmcnt(0)
	s_add_i32 s10, s19, s4
	s_and_b32 s4, s10, -8
	s_sub_i32 s8, s19, s4
	s_cmp_gt_i32 s8, -1
	s_cbranch_scc0 .LBB0_1338
	s_lshl_b32 s9, s8, 6
	s_ashr_i32 s4, s10, 3
	s_cbranch_execz .LBB0_1339
	s_branch .LBB0_1340

; __device__ __forceinline__ int opq(int v) { asm volatile("" : "+v"(v)); return v; }
; __device__ __forceinline__ int lane_id() { return (int)__builtin_amdgcn_mbcnt_hi(~0u, __builtin_amdgcn_mbcnt_lo(~0u, 0u)); }
; template <class Epi, class Sched, bool ALIGN_EPI, bool F8 = false>
; __device__ __forceinline__ void gemm_phase(LAS unsigned char* lds, const Gemm g, const Sched& S, const Epi& E) {
;     const int wid = __builtin_amdgcn_readfirstlane(g.wave), tid = opq((wid << 6) | lane_id()), lane = tid & 63, wr = wid >> 2, wc = wid & 3, fr = lane & 15, fq = lane >> 4;
;     const int K = g.K, nt = K / BK;
;     unsigned voffA[2], voffB[2];
; #pragma unroll
;     for (int i = 0; i < 2; ++i) { int R, C; stage_rc(tid * 16 + i * 8192, R, C); const int Rb = (R & ~31) + perm32(R & 31);
;         voffA[i] = (unsigned)(R * g.lda + C) * 2u; voffB[i] = (unsigned)(Rb * g.ldb + C) * 2u; }
;     const unsigned kstep = (unsigned)(BK * 2);
;     const unsigned hstepA = (unsigned)HALF * g.lda * 2u, hstepB = (unsigned)HALF * g.ldb * 2u;
;     const unsigned tstepA = 2u * hstepA, tstepB = 2u * hstepB;
;     const unsigned ldsw = (unsigned)wid * 1024u;
;     const unsigned lds_w32 = (unsigned)__builtin_amdgcn_readfirstlane((int)((unsigned)(uintptr_t)lds + ldsw));
;     constexpr int KOFF = F8 ? 16 : 1024;
;     const int aoff = lds_byte(wr * 64 + fr, F8 ? fq * 16 : fq * 8), boff = lds_byte(wc * 32 + fr, F8 ? fq * 16 : fq * 8);
;     ...
;     Unit cur, nxt; int ui = 0;
;     if (!S.next(0, cur)) return;
;     f32x4 acc[2][2][4][2];
; #pragma unroll
;     for (int a = 0; a < 2; ++a)
; #pragma unroll
;         for (int b = 0; b < 2; ++b)
; #pragma unroll
;             for (int m = 0; m < 4; ++m)
; #pragma unroll
;                 for (int n = 0; n < 2; ++n) acc[a][b][m][n] = (f32x4){0.f, 0.f, 0.f, 0.f};
;     v8i_t At[4], B0[2], B1[2];
;     unsigned cA = (unsigned)cur.pm * tstepA + (unsigned)cur.z * (unsigned)g.zA, cB = (unsigned)cur.pn * tstepB + (unsigned)cur.z * (unsigned)g.zB;
;     __amdgpu_buffer_rsrc_t rsA = __builtin_amdgcn_make_buffer_rsrc((void*)g.A, 0, 0x7fffffff, 0x00020000), rsB = __builtin_amdgcn_make_buffer_rsrc((void*)g.Bt, 0, 0x7fffffff, 0x00020000); (void)rsA; (void)rsB;
;     PG8_STAGE_B(PG8_SB(0, 0), cB); PG8_STAGE_B(PG8_SB(0, 1), cB + hstepB); PG8_STAGE_A(PG8_SA(0, 0), cA); PG8_STAGE_A(PG8_SA(0, 1), cA + hstepA);
;     if (wr == 1) PG8_BAR;
.LBB0_1341:
	s_xor_b32 s19, s19, s97
	s_waitcnt lgkmcnt(0)
	s_load_dwordx4 s[8:11], s[0:1], 0x98
	s_andn2_b64 vcc, exec, s[2:3]
	s_cbranch_vccnz .LBB0_1377
	v_bfe_i32 v2, v0, 27, 1
	v_lshlrev_b32_e32 v4, 4, v0
	v_lshrrev_b32_e32 v2, 22, v2
	v_add_u32_e32 v2, v4, v2
	v_and_b32_e32 v2, 0xfffffc00, v2
	v_sub_u32_e32 v2, v4, v2
	v_lshrrev_b32_e32 v3, 4, v2
	v_bitop3_b32 v3, v3, v2, 32 bitop3:0x6c
	v_ashrrev_i32_e32 v2, 31, v2
	v_lshrrev_b32_e32 v2, 26, v2
	v_ashrrev_i32_e32 v1, 31, v0
	v_add_u32_e32 v2, v3, v2
	v_lshrrev_b32_e32 v1, 26, v1
	v_ashrrev_i32_e32 v2, 6, v2
	v_add_u32_e32 v1, v0, v1
	v_mul_i32_i24_e32 v7, 64, v2
	v_ashrrev_i32_e32 v1, 6, v1
	v_sub_u32_e32 v3, v3, v7
	v_mov_b32_e32 v7, 1
	v_lshlrev_b32_e32 v5, 3, v1
	v_lshlrev_b32_e32 v6, 5, v1
	v_ashrrev_i16_sdwa v3, v7, sext(v3) dst_sel:DWORD dst_unused:UNUSED_PAD src0_sel:DWORD src1_sel:BYTE_0
	v_and_b32_e32 v5, -16, v5
	v_and_b32_e32 v6, 32, v6
	v_bfe_i32 v3, v3, 0, 16
	v_add_u32_e32 v5, v2, v5
	v_and_b32_e32 v10, 3, v2
	s_mov_b32 s0, 0xfffe0
	v_add_lshl_u32 v6, v6, v3, 1
	v_lshlrev_b32_e32 v8, 1, v5
	v_lshrrev_b32_e32 v9, 2, v5
	v_and_or_b32 v10, v5, s0, v10
	v_lshl_add_u32 v163, v5, 12, v6
	v_add_u32_e32 v5, 0x2000, v4
	v_ashrrev_i32_e32 v4, 31, v5
	v_lshrrev_b32_e32 v4, 22, v4
	v_and_b32_e32 v8, 24, v8
	v_and_b32_e32 v9, 4, v9
	v_add_u32_e32 v4, v5, v4
	v_or3_b32 v8, v10, v9, v8
	v_ashrrev_i32_e32 v4, 10, v4
	v_lshl_add_u32 v164, v8, 12, v6
	v_mul_i32_i24_e32 v6, 0x400, v4
	v_sub_u32_e32 v5, v5, v6
	v_lshrrev_b32_e32 v6, 4, v5
	v_bitop3_b32 v6, v6, v5, 32 bitop3:0x6c
	v_lshlrev_b32_e32 v5, 3, v4
	v_and_b32_e32 v8, -16, v5
	v_ashrrev_i32_e32 v5, 31, v6
	v_lshrrev_b32_e32 v5, 26, v5
	v_add_u32_e32 v9, v6, v5
	s_waitcnt lgkmcnt(0)
	s_add_u32 s12, s10, 0x1af00000
	v_ashrrev_i32_e32 v5, 6, v9
	v_and_b32_e32 v9, 0xc0, v9
	s_addc_u32 s13, s11, 0
	v_add_u32_e32 v8, v5, v8
	v_sub_u32_e32 v6, v6, v9
	s_add_u32 s14, s10, 0x9c00000
	v_lshlrev_b32_e32 v10, 5, v4
	v_ashrrev_i16_sdwa v6, v7, sext(v6) dst_sel:DWORD dst_unused:UNUSED_PAD src0_sel:DWORD src1_sel:BYTE_0
	v_lshlrev_b32_e32 v7, 1, v8
	v_lshrrev_b32_e32 v9, 2, v8
	v_and_b32_e32 v11, 3, v5
	v_readlane_b32 s1, v254, 15
	s_addc_u32 s15, s11, 0
	v_and_b32_e32 v10, 32, v10
	v_bfe_i32 v6, v6, 0, 16
	v_and_b32_e32 v7, 24, v7
	v_and_b32_e32 v9, 4, v9
	v_and_or_b32 v11, v8, s0, v11
	s_lshl_b32 s33, s1, 10
	v_or3_b32 v7, v11, v9, v7
	v_add_lshl_u32 v9, v10, v6, 1
	s_lshl_b32 s54, s4, 20
	s_add_i32 s36, s33, 0
	v_lshl_add_u32 v166, v7, 12, v9
	s_add_i32 m0, s36, 0x10000
	v_add_u32_e32 v7, s54, v164
	global_load_lds_dwordx4 v7, s[14:15]
	v_add_u32_e32 v7, s54, v166
	s_add_i32 m0, s36, 0x12000
	s_or_b32 s0, s54, 0x80000
	global_load_lds_dwordx4 v7, s[14:15]
	s_add_i32 m0, s36, 0x14000
	v_add_u32_e32 v7, s0, v164
	global_load_lds_dwordx4 v7, s[14:15]
	v_add_u32_e32 v7, s0, v166
	s_add_i32 m0, s36, 0x16000
	s_lshl_b32 s55, s5, 20
	v_lshl_add_u32 v165, v8, 12, v9
	global_load_lds_dwordx4 v7, s[14:15]
	v_add_u32_e32 v7, s55, v163
	s_mov_b32 m0, s36
	s_add_i32 s37, s36, 0x2000
	global_load_lds_dwordx4 v7, s[12:13]
	v_add_u32_e32 v7, s55, v165
	s_mov_b32 m0, s37
	s_or_b32 s0, s55, 0x80000
	s_add_i32 s38, s36, 0x4000
	global_load_lds_dwordx4 v7, s[12:13]
	v_add_u32_e32 v7, s0, v163
	s_mov_b32 m0, s38
	s_add_i32 s39, s36, 0x6000
	global_load_lds_dwordx4 v7, s[12:13]
	v_add_u32_e32 v7, s0, v165
	s_mov_b32 m0, s39
	s_ashr_i32 s0, s1, 2
	global_load_lds_dwordx4 v7, s[12:13]
	s_cmp_eq_u32 s0, 1
	s_cselect_b64 s[16:17], -1, 0
	s_cmp_lg_u32 s0, 1
	s_mov_b32 s40, 0
	s_cbranch_scc1 .LBB0_1344
	s_barrier

;     __device__ bool next(int i, Unit& u) const { if (!S.next(i >> 1, u)) return false; u.z = i & 1; return true; }
;     __device__ bool next(int i, Unit& u) const { if (!S.next(i, u)) return false; u.z = z; return true; }
;     __device__ bool next(int i, Unit& u) const {
;         const long L = (long)i * G + c; if (L >= nwg) return false;
;         int wgid = (int)L; { const int q = nwg / NXCD, r = nwg % NXCD, xcd = wgid % NXCD, off = wgid / NXCD; wgid = (xcd < r ? xcd * (q + 1) : r * (q + 1) + (xcd - r) * q) + off; }
;         const int nR = tr ? nN : nM, nS = tr ? nM : nN;
;         const int nig = wgm * nS, gid = wgid / nig, f0 = gid * wgm, gsz = (nR - f0) < wgm ? (nR - f0) : wgm;
;         const int pr = f0 + ((wgid % nig) % gsz), ps = (wgid % nig) / gsz;
;         u.pm = tr ? ps : pr; u.pn = tr ? pr : ps; u.z = 0; return true;
; template <class Epi, class Sched, bool ALIGN_EPI, bool F8 = false>
; __device__ __forceinline__ void gemm_phase(LAS unsigned char* lds, const Gemm g, const Sched& S, const Epi& E) {
;     ...
;         const bool has_next = S.next(ui + 1, nxt);
;         const unsigned nA = has_next ? (unsigned)nxt.pm * tstepA + (unsigned)nxt.z * (unsigned)g.zA : cA;
;         const unsigned nB = has_next ? (unsigned)nxt.pn * tstepB + (unsigned)nxt.z * (unsigned)g.zB : cB;
.LBB0_1347:
	s_add_i32 s40, s40, 1
	s_mul_i32 s0, s40, s45
	s_mul_hi_u32 s1, s40, s18
	s_add_i32 s1, s1, s0
	s_mul_i32 s0, s40, s18
	s_add_u32 s0, s0, s19
	s_addc_u32 s1, s1, s46
	s_cmp_eq_u32 s18, 0x100
	s_cselect_b32 s97, 0x100, 0
	s_xor_b32 s0, s0, s97
	v_cmp_gt_i64_e32 vcc, s[0:1], v[138:139]
	v_cmp_lt_i64_e64 s[2:3], s[0:1], v[136:137]
	s_cbranch_vccnz .LBB0_1353
	s_ashr_i32 s1, s0, 31
	s_lshr_b32 s1, s1, 29
	s_add_i32 s50, s0, s1
	s_and_b32 s1, s50, -8
	s_sub_i32 s51, s0, s1
	s_cmp_gt_i32 s51, -1
	s_mov_b64 s[0:1], -1
	s_cbranch_scc0 .LBB0_1350
	s_lshl_b32 s52, s51, 6
	s_mov_b64 s[0:1], 0

;     __device__ bool next(int i, Unit& u) const { if (!S.next(i >> 1, u)) return false; u.z = i & 1; return true; }
;     __device__ bool next(int i, Unit& u) const { if (!S.next(i, u)) return false; u.z = z; return true; }
; #define PHASE_BEGIN() P.reload(launder_s(kargs)); const int G = sopq(G0), bx = sopq(bx0); const int lane = opq(lane_id()); const int gw = bx * 8 + wave, NGW = G * 8; (void)gw; (void)NGW; (void)lane
; #define PHASE_BEGIN() P.reload(launder_s(kargs)); const int G = sopq(G0), bx = sopq(bx0); const int lane = opq(lane_id()); const int gw = bx * 8 + wave, NGW = G * 8; (void)gw; (void)NGW; (void)lane
;     __device__ bool next(int i, Unit& u) const {
;         const long L = (long)i * G + c; if (L >= nwg) return false;
;         int wgid = (int)L; { const int q = nwg / NXCD, r = nwg % NXCD, xcd = wgid % NXCD, off = wgid / NXCD; wgid = (xcd < r ? xcd * (q + 1) : r * (q + 1) + (xcd - r) * q) + off; }
;         const int nR = tr ? nN : nM, nS = tr ? nM : nN;
;         const int nig = wgm * nS, gid = wgid / nig, f0 = gid * wgm, gsz = (nR - f0) < wgm ? (nR - f0) : wgm;
;         const int pr = f0 + ((wgid % nig) % gsz), ps = (wgid % nig) / gsz;
;         u.pm = tr ? ps : pr; u.pn = tr ? pr : ps; u.z = 0; return true;
; template <int l> __device__ __forceinline__ void layer_phases(LAS unsigned char* lds, Ptrs& P, const XcdBarrier& xbar, KArgs kargs, const int lo, const int hi, const int lane0, const int wave, const int G0, const int bx0) {
;     ...
;         if (IN(pb + 7)) {
;             PHASE_BEGIN();
;             pg8::Gemm g{P.XB1(), P.WPG() + (size_t)l * DM * DM, DM, DM, DM, 0, 0, P.wave}; pg8::StaticOrder S; S.init(M, DM, G, bx, WGM_BF);
;             pg8::EpiPle E{P.X1(), P.T(), P.SSQ() + (size_t)(1 + 2 * l) * M, P.out, P.XB(), P.XB8(), P.SSQ() + (size_t)(2 + 2 * l) * M, l + 1 < DEPTH};
;     ...
;             pg8::gemm_phase<pg8::EpiPle, pg8::StaticOrder, true>(lds, g, S, E);
.LBB0_2186:
	v_readlane_b32 s0, v254, 0
	v_readlane_b32 s2, v254, 2
	s_cmp_lt_i32 s2, 17
	v_readlane_b32 s1, v254, 1
	s_waitcnt lgkmcnt(0)
	s_cselect_b64 s[12:13], -1, 0
	s_and_b64 s[0:1], s[12:13], s[44:45]
	s_andn2_b64 vcc, exec, s[0:1]
	v_readlane_b32 s3, v254, 3
	s_cbranch_vccnz .LBB0_2229
	s_waitcnt vmcnt(0)
	v_mbcnt_lo_u32_b32 v0, -1, 0
	v_readlane_b32 s0, v254, 7
	v_readlane_b32 s2, v254, 4
	v_mbcnt_hi_u32_b32 v160, -1, v0
	v_readlane_b32 s1, v254, 8
	s_mov_b32 s18, s2
	s_mov_b32 s19, s79
	s_cmp_eq_u32 s18, 0x100
	s_cselect_b32 s97, 0x100, 0
	s_xor_b32 s19, s19, s97
	v_mov_b32_e32 v0, v160
	v_readlane_b32 s3, v254, 5
	v_readlane_b32 s2, v254, 15
	s_cmpk_lt_i32 s19, 0x200
	s_nop 0
	v_lshl_or_b32 v0, s2, 6, v160
	s_cselect_b64 s[2:3], -1, 0
	s_cmpk_gt_i32 s19, 0x1ff
	s_cbranch_scc1 .LBB0_2193
	s_ashr_i32 s4, s19, 31
	s_lshr_b32 s4, s4, 29
	s_add_i32 s8, s19, s4
	s_and_b32 s4, s8, -8
	s_sub_i32 s6, s19, s4
	s_cmp_gt_i32 s6, -1
	s_cbranch_scc0 .LBB0_2190
	s_lshl_b32 s7, s6, 6
	s_ashr_i32 s4, s8, 3
	s_cbranch_execz .LBB0_2191
	s_branch .LBB0_2192

; __device__ __forceinline__ int opq(int v) { asm volatile("" : "+v"(v)); return v; }
; __device__ __forceinline__ int lane_id() { return (int)__builtin_amdgcn_mbcnt_hi(~0u, __builtin_amdgcn_mbcnt_lo(~0u, 0u)); }
; template <class Epi, class Sched, bool ALIGN_EPI, bool F8 = false>
; __device__ __forceinline__ void gemm_phase(LAS unsigned char* lds, const Gemm g, const Sched& S, const Epi& E) {
;     const int wid = __builtin_amdgcn_readfirstlane(g.wave), tid = opq((wid << 6) | lane_id()), lane = tid & 63, wr = wid >> 2, wc = wid & 3, fr = lane & 15, fq = lane >> 4;
;     const int K = g.K, nt = K / BK;
;     unsigned voffA[2], voffB[2];
; #pragma unroll
;     for (int i = 0; i < 2; ++i) { int R, C; stage_rc(tid * 16 + i * 8192, R, C); const int Rb = (R & ~31) + perm32(R & 31);
;         voffA[i] = (unsigned)(R * g.lda + C) * 2u; voffB[i] = (unsigned)(Rb * g.ldb + C) * 2u; }
;     const unsigned kstep = (unsigned)(BK * 2);
;     const unsigned hstepA = (unsigned)HALF * g.lda * 2u, hstepB = (unsigned)HALF * g.ldb * 2u;
;     const unsigned tstepA = 2u * hstepA, tstepB = 2u * hstepB;
;     const unsigned ldsw = (unsigned)wid * 1024u;
;     const unsigned lds_w32 = (unsigned)__builtin_amdgcn_readfirstlane((int)((unsigned)(uintptr_t)lds + ldsw));
;     constexpr int KOFF = F8 ? 16 : 1024;
;     const int aoff = lds_byte(wr * 64 + fr, F8 ? fq * 16 : fq * 8), boff = lds_byte(wc * 32 + fr, F8 ? fq * 16 : fq * 8);
;     ...
;     Unit cur, nxt; int ui = 0;
;     if (!S.next(0, cur)) return;
;     f32x4 acc[2][2][4][2];
; #pragma unroll
;     for (int a = 0; a < 2; ++a)
; #pragma unroll
;         for (int b = 0; b < 2; ++b)
; #pragma unroll
;             for (int m = 0; m < 4; ++m)
; #pragma unroll
;                 for (int n = 0; n < 2; ++n) acc[a][b][m][n] = (f32x4){0.f, 0.f, 0.f, 0.f};
;     v8i_t At[4], B0[2], B1[2];
;     unsigned cA = (unsigned)cur.pm * tstepA + (unsigned)cur.z * (unsigned)g.zA, cB = (unsigned)cur.pn * tstepB + (unsigned)cur.z * (unsigned)g.zB;
;     __amdgpu_buffer_rsrc_t rsA = __builtin_amdgcn_make_buffer_rsrc((void*)g.A, 0, 0x7fffffff, 0x00020000), rsB = __builtin_amdgcn_make_buffer_rsrc((void*)g.Bt, 0, 0x7fffffff, 0x00020000); (void)rsA; (void)rsB;
;     PG8_STAGE_B(PG8_SB(0, 0), cB); PG8_STAGE_B(PG8_SB(0, 1), cB + hstepB); PG8_STAGE_A(PG8_SA(0, 0), cA); PG8_STAGE_A(PG8_SA(0, 1), cA + hstepA);
;     if (wr == 1) PG8_BAR;
.LBB0_2193:
	s_xor_b32 s19, s19, s97
	s_load_dwordx4 s[8:11], s[0:1], 0x98
	s_andn2_b64 vcc, exec, s[2:3]
	s_cbranch_vccnz .LBB0_2229
	v_bfe_i32 v2, v0, 27, 1
	v_lshlrev_b32_e32 v4, 4, v0
	v_lshrrev_b32_e32 v2, 22, v2
	v_add_u32_e32 v2, v4, v2
	v_and_b32_e32 v2, 0xfffffc00, v2
	v_sub_u32_e32 v2, v4, v2
	v_lshrrev_b32_e32 v3, 4, v2
	v_bitop3_b32 v3, v3, v2, 32 bitop3:0x6c
	v_ashrrev_i32_e32 v2, 31, v2
	v_lshrrev_b32_e32 v2, 26, v2
	v_ashrrev_i32_e32 v1, 31, v0
	v_add_u32_e32 v2, v3, v2
	v_lshrrev_b32_e32 v1, 26, v1
	v_ashrrev_i32_e32 v2, 6, v2
	v_add_u32_e32 v1, v0, v1
	v_mul_i32_i24_e32 v7, 64, v2
	v_ashrrev_i32_e32 v1, 6, v1
	v_sub_u32_e32 v3, v3, v7
	v_mov_b32_e32 v7, 1
	v_lshlrev_b32_e32 v5, 3, v1
	v_lshlrev_b32_e32 v6, 5, v1
	v_ashrrev_i16_sdwa v3, v7, sext(v3) dst_sel:DWORD dst_unused:UNUSED_PAD src0_sel:DWORD src1_sel:BYTE_0
	v_and_b32_e32 v5, -16, v5
	v_and_b32_e32 v6, 32, v6
	v_bfe_i32 v3, v3, 0, 16
	v_add_u32_e32 v5, v2, v5
	v_and_b32_e32 v10, 3, v2
	s_mov_b32 s0, 0xfffe0
	v_add_lshl_u32 v6, v6, v3, 1
	v_lshlrev_b32_e32 v8, 1, v5
	v_lshrrev_b32_e32 v9, 2, v5
	v_and_or_b32 v10, v5, s0, v10
	v_lshl_add_u32 v161, v5, 12, v6
	v_add_u32_e32 v5, 0x2000, v4
	v_ashrrev_i32_e32 v4, 31, v5
	v_lshrrev_b32_e32 v4, 22, v4
	v_and_b32_e32 v8, 24, v8
	v_and_b32_e32 v9, 4, v9
	v_add_u32_e32 v4, v5, v4
	v_or3_b32 v8, v10, v9, v8
	v_ashrrev_i32_e32 v4, 10, v4
	v_lshl_add_u32 v162, v8, 12, v6
	v_mul_i32_i24_e32 v6, 0x400, v4
	v_sub_u32_e32 v5, v5, v6
	v_lshrrev_b32_e32 v6, 4, v5
	v_bitop3_b32 v6, v6, v5, 32 bitop3:0x6c
	v_lshlrev_b32_e32 v5, 3, v4
	v_and_b32_e32 v8, -16, v5
	v_ashrrev_i32_e32 v5, 31, v6
	v_lshrrev_b32_e32 v5, 26, v5
	v_add_u32_e32 v9, v6, v5
	s_waitcnt lgkmcnt(0)
	s_add_u32 s14, s10, 0x1af00000
	v_ashrrev_i32_e32 v5, 6, v9
	v_and_b32_e32 v9, 0xc0, v9
	s_addc_u32 s15, s11, 0
	v_add_u32_e32 v8, v5, v8
	v_sub_u32_e32 v6, v6, v9
	s_add_u32 s16, s10, 0xa400000
	v_lshlrev_b32_e32 v10, 5, v4
	v_ashrrev_i16_sdwa v6, v7, sext(v6) dst_sel:DWORD dst_unused:UNUSED_PAD src0_sel:DWORD src1_sel:BYTE_0
	v_lshlrev_b32_e32 v7, 1, v8
	v_lshrrev_b32_e32 v9, 2, v8
	v_and_b32_e32 v11, 3, v5
	v_readlane_b32 s1, v254, 15
	s_addc_u32 s17, s11, 0
	v_and_b32_e32 v10, 32, v10
	v_bfe_i32 v6, v6, 0, 16
	v_and_b32_e32 v7, 24, v7
	v_and_b32_e32 v9, 4, v9
	v_and_or_b32 v11, v8, s0, v11
	s_lshl_b32 s33, s1, 10
	v_or3_b32 v7, v11, v9, v7
	v_add_lshl_u32 v9, v10, v6, 1
	s_lshl_b32 s6, s4, 20
	s_add_i32 s34, s33, 0
	v_lshl_add_u32 v164, v7, 12, v9
	s_add_i32 m0, s34, 0x10000
	v_add_u32_e32 v7, s6, v162
	global_load_lds_dwordx4 v7, s[16:17]
	v_add_u32_e32 v7, s6, v164
	s_add_i32 m0, s34, 0x12000
	s_or_b32 s0, s6, 0x80000
	global_load_lds_dwordx4 v7, s[16:17]
	s_add_i32 m0, s34, 0x14000
	v_add_u32_e32 v7, s0, v162
	global_load_lds_dwordx4 v7, s[16:17]
	v_add_u32_e32 v7, s0, v164
	s_add_i32 m0, s34, 0x16000
	s_lshl_b32 s7, s5, 20
	v_lshl_add_u32 v163, v8, 12, v9
	global_load_lds_dwordx4 v7, s[16:17]
	v_add_u32_e32 v7, s7, v161
	s_mov_b32 m0, s34
	s_add_i32 s35, s34, 0x2000
	global_load_lds_dwordx4 v7, s[14:15]
	v_add_u32_e32 v7, s7, v163
	s_mov_b32 m0, s35
	s_or_b32 s0, s7, 0x80000
	s_add_i32 s36, s34, 0x4000
	global_load_lds_dwordx4 v7, s[14:15]
	v_add_u32_e32 v7, s0, v161
	s_mov_b32 m0, s36
	s_add_i32 s37, s34, 0x6000
	global_load_lds_dwordx4 v7, s[14:15]
	v_add_u32_e32 v7, s0, v163
	s_mov_b32 m0, s37
	s_ashr_i32 s0, s1, 2
	global_load_lds_dwordx4 v7, s[14:15]
	s_cmp_eq_u32 s0, 1
	s_cselect_b64 s[20:21], -1, 0
	s_cmp_lg_u32 s0, 1
	s_mov_b32 s38, 0
	s_cbranch_scc1 .LBB0_2196
	s_barrier

;     __device__ bool next(int i, Unit& u) const { if (!S.next(i >> 1, u)) return false; u.z = i & 1; return true; }
;     __device__ bool next(int i, Unit& u) const { if (!S.next(i, u)) return false; u.z = z; return true; }
;     __device__ bool next(int i, Unit& u) const {
;         const long L = (long)i * G + c; if (L >= nwg) return false;
;         int wgid = (int)L; { const int q = nwg / NXCD, r = nwg % NXCD, xcd = wgid % NXCD, off = wgid / NXCD; wgid = (xcd < r ? xcd * (q + 1) : r * (q + 1) + (xcd - r) * q) + off; }
;         const int nR = tr ? nN : nM, nS = tr ? nM : nN;
;         const int nig = wgm * nS, gid = wgid / nig, f0 = gid * wgm, gsz = (nR - f0) < wgm ? (nR - f0) : wgm;
;         const int pr = f0 + ((wgid % nig) % gsz), ps = (wgid % nig) / gsz;
;         u.pm = tr ? ps : pr; u.pn = tr ? pr : ps; u.z = 0; return true;
; template <class Epi, class Sched, bool ALIGN_EPI, bool F8 = false>
; __device__ __forceinline__ void gemm_phase(LAS unsigned char* lds, const Gemm g, const Sched& S, const Epi& E) {
;     ...
;         const bool has_next = S.next(ui + 1, nxt);
;         const unsigned nA = has_next ? (unsigned)nxt.pm * tstepA + (unsigned)nxt.z * (unsigned)g.zA : cA;
;         const unsigned nB = has_next ? (unsigned)nxt.pn * tstepB + (unsigned)nxt.z * (unsigned)g.zB : cB;
.LBB0_2199:
	s_add_i32 s38, s38, 1
	s_mul_i32 s0, s38, s43
	s_mul_hi_u32 s1, s38, s18
	s_add_i32 s1, s1, s0
	s_mul_i32 s0, s38, s18
	s_add_u32 s0, s0, s19
	s_addc_u32 s1, s1, s44
	s_cmp_eq_u32 s18, 0x100
	s_cselect_b32 s97, 0x100, 0
	s_xor_b32 s0, s0, s97
	v_cmp_gt_i64_e32 vcc, s[0:1], v[130:131]
	v_cmp_lt_i64_e64 s[2:3], s[0:1], v[128:129]
	s_cbranch_vccnz .LBB0_2205
	s_ashr_i32 s1, s0, 31
	s_lshr_b32 s1, s1, 29
	s_add_i32 s48, s0, s1
	s_and_b32 s1, s48, -8
	s_sub_i32 s49, s0, s1
	s_cmp_gt_i32 s49, -1
	s_mov_b64 s[0:1], -1
	s_cbranch_scc0 .LBB0_2202
	s_lshl_b32 s50, s49, 6
	s_mov_b64 s[0:1], 0
